# diff-attn unit prologue: fragment prefetch with counted waits in the two peeled QK blocks
# speedup vs baseline: 1.0017x; 1.0017x over previous
.LBB0_305:
	v_mov_b32_e32 v5, s18
	s_movk_i32 s2, 0x90
	v_mad_u32_u24 v4, v4, s2, v5
	v_add3_u32 v166, v4, v168, 0
	ds_read_b128 v[112:115], v162
	ds_read_b128 v[4:7], v166
	ds_read_b128 v[8:11], v166 offset:4608
	ds_read_b128 v[116:119], v162 offset:1024
	ds_read_b128 v[12:15], v166 offset:32
	ds_read_b128 v[56:59], v166 offset:4640
	ds_read_b128 v[120:123], v162 offset:2048
	ds_read_b128 v[60:63], v166 offset:64
	ds_read_b128 v[220:223], v166 offset:4672
	ds_read_b128 v[124:127], v162 offset:3072
	ds_read_b128 v[224:227], v166 offset:96
	ds_read_b128 v[228:231], v166 offset:4704
	s_mov_b64 s[2:3], 0x800
	s_cmp_gt_i32 s22, 0
	v_lshl_add_u64 v[2:3], v[2:3], 0, s[2:3]
	s_cselect_b64 s[14:15], -1, 0
	s_cmp_lt_i32 s22, 1
	s_waitcnt lgkmcnt(10)
	v_mfma_f32_32x32x16_bf16 v[16:31], v[4:7], v[112:115], v[16:31]
	s_waitcnt lgkmcnt(9)
	v_mfma_f32_32x32x16_bf16 v[32:47], v[8:11], v[112:115], v[32:47]
	s_waitcnt lgkmcnt(7)
	v_mfma_f32_32x32x16_bf16 v[16:31], v[12:15], v[116:119], v[16:31]
	s_waitcnt lgkmcnt(6)
	v_mfma_f32_32x32x16_bf16 v[32:47], v[56:59], v[116:119], v[32:47]
	s_waitcnt lgkmcnt(4)
	v_mfma_f32_32x32x16_bf16 v[16:31], v[60:63], v[120:123], v[16:31]
	s_waitcnt lgkmcnt(3)
	v_mfma_f32_32x32x16_bf16 v[32:47], v[220:223], v[120:123], v[32:47]
	s_waitcnt lgkmcnt(0)
	s_barrier
	v_mfma_f32_32x32x16_bf16 v[16:31], v[224:227], v[124:127], v[16:31]
	v_mfma_f32_32x32x16_bf16 v[32:47], v[228:231], v[124:127], v[32:47]
	s_cbranch_scc1 .LBB0_307
	v_add_co_u32_e32 v4, vcc, 0xc0000, v2
	s_nop 1
	v_addc_co_u32_e32 v5, vcc, 0, v3, vcc
	global_load_dwordx4 v[48:51], v[4:5], off
	global_load_dwordx4 v[52:55], v[4:5], off offset:128

.LBB0_318:
	ds_read_b128 v[232:235], v162
	ds_read_b128 v[134:137], v166 offset:18432
	ds_read_b128 v[138:141], v166 offset:23040
	ds_read_b128 v[236:239], v162 offset:1024
	ds_read_b128 v[192:195], v166 offset:18464
	ds_read_b128 v[196:199], v166 offset:23072
	ds_read_b128 v[240:243], v162 offset:2048
	ds_read_b128 v[200:203], v166 offset:18496
	ds_read_b128 v[204:207], v166 offset:23104
	ds_read_b128 v[244:247], v162 offset:3072
	ds_read_b128 v[220:223], v166 offset:18528
	ds_read_b128 v[224:227], v166 offset:23136
	s_and_b64 vcc, exec, s[2:3]
	s_waitcnt lgkmcnt(10)
	v_mfma_f32_32x32x16_bf16 v[64:79], v[134:137], v[232:235], v[64:79]
	s_waitcnt lgkmcnt(9)
	v_mfma_f32_32x32x16_bf16 v[80:95], v[138:141], v[232:235], v[80:95]
	s_waitcnt lgkmcnt(7)
	v_mfma_f32_32x32x16_bf16 v[64:79], v[192:195], v[236:239], v[64:79]
	s_waitcnt lgkmcnt(6)
	v_mfma_f32_32x32x16_bf16 v[80:95], v[196:199], v[236:239], v[80:95]
	s_waitcnt lgkmcnt(4)
	v_mfma_f32_32x32x16_bf16 v[64:79], v[200:203], v[240:243], v[64:79]
	s_waitcnt lgkmcnt(3)
	v_mfma_f32_32x32x16_bf16 v[80:95], v[204:207], v[240:243], v[80:95]
	s_waitcnt lgkmcnt(1)
	v_mfma_f32_32x32x16_bf16 v[64:79], v[220:223], v[244:247], v[64:79]
	s_waitcnt lgkmcnt(0)
	v_mfma_f32_32x32x16_bf16 v[80:95], v[224:227], v[244:247], v[80:95]
	s_cbranch_vccnz .LBB0_320
	s_waitcnt vmcnt(3)
	ds_write_b128 v163, v[48:51]
	s_waitcnt vmcnt(2)
	ds_write_b128 v163, v[52:55] offset:9216
